# v28 plus phase-0 transpose loops unrolled by two k-steps: 32 loads in flight per wait (2 round trips per item instead of 4)
# baseline (speedup 1.0000x reference)
; DI void transpose_item(const float* W, int N, const float* gain, bf16_t* WT, int ldk, int k0, int n0, int drow0, LAS float* scr, int lane) {
; #pragma unroll 8
;     for (int i = 0; i < 32; ++i) { const int kk = 2 * i + (lane >> 5); const float g = gain ? gain[k0 + kk] : 1.f; scr[kk * 33 + (lane & 31)] = W[(size_t)(k0 + kk) * N + n0 + (lane & 31)] * g; }
;     asm volatile("s_waitcnt lgkmcnt(0)" ::: "memory");
.LBB0_31:
	v_mov_b32_e32 v100, 1.0
	v_mov_b32_e32 v101, 1.0
	v_mov_b32_e32 v102, 1.0
	v_mov_b32_e32 v103, 1.0
	v_mov_b32_e32 v104, 1.0
	v_mov_b32_e32 v105, 1.0
	v_mov_b32_e32 v106, 1.0
	v_mov_b32_e32 v107, 1.0
	v_mov_b32_e32 v108, 1.0
	v_mov_b32_e32 v109, 1.0
	v_mov_b32_e32 v110, 1.0
	v_mov_b32_e32 v111, 1.0
	v_mov_b32_e32 v112, 1.0
	v_mov_b32_e32 v113, 1.0
	v_mov_b32_e32 v114, 1.0
	v_mov_b32_e32 v115, 1.0
	s_andn2_b64 vcc, exec, s[26:27]
	s_cbranch_vccnz .Ltr2_a_ng0
	v_lshl_add_u64 v[148:149], s[36:37], 0, v[38:39]
	v_lshl_add_u64 v[150:151], s[36:37], 0, v[24:25]
	global_load_dword v100, v[148:149], off
	global_load_dword v101, v[150:151], off offset:8
	global_load_dword v102, v[150:151], off offset:16
	global_load_dword v103, v[150:151], off offset:24
	global_load_dword v104, v[150:151], off offset:32
	global_load_dword v105, v[150:151], off offset:40
	global_load_dword v106, v[150:151], off offset:48
	global_load_dword v107, v[150:151], off offset:56
.Ltr2_a_ng0:
	v_lshl_add_u64 v[132:133], v[40:41], 0, s[34:35]
	v_lshl_add_u64 v[134:135], v[36:37], 0, s[34:35]
	v_lshl_add_u64 v[136:137], v[34:35], 0, s[34:35]
	v_lshl_add_u64 v[138:139], v[32:33], 0, s[34:35]
	v_lshl_add_u64 v[140:141], v[30:31], 0, s[34:35]
	v_lshl_add_u64 v[142:143], v[28:29], 0, s[34:35]
	v_lshl_add_u64 v[144:145], v[26:27], 0, s[34:35]
	v_lshl_add_u64 v[146:147], v[22:23], 0, s[34:35]
	global_load_dword v116, v[132:133], off
	global_load_dword v117, v[134:135], off
	global_load_dword v118, v[136:137], off
	global_load_dword v119, v[138:139], off
	global_load_dword v120, v[140:141], off
	global_load_dword v121, v[142:143], off
	global_load_dword v122, v[144:145], off
	global_load_dword v123, v[146:147], off
	s_add_u32 s34, s34, 0x2c000
	s_addc_u32 s35, s35, 0
	s_add_u32 s36, s36, 64
	s_addc_u32 s37, s37, 0
	s_andn2_b64 vcc, exec, s[26:27]
	s_cbranch_vccnz .Ltr2_a_ng1
	v_lshl_add_u64 v[156:157], s[36:37], 0, v[38:39]
	v_lshl_add_u64 v[158:159], s[36:37], 0, v[24:25]
	global_load_dword v108, v[156:157], off
	global_load_dword v109, v[158:159], off offset:8
	global_load_dword v110, v[158:159], off offset:16
	global_load_dword v111, v[158:159], off offset:24
	global_load_dword v112, v[158:159], off offset:32
	global_load_dword v113, v[158:159], off offset:40
	global_load_dword v114, v[158:159], off offset:48
	global_load_dword v115, v[158:159], off offset:56
.Ltr2_a_ng1:
	v_lshl_add_u64 v[160:161], v[40:41], 0, s[34:35]
	v_lshl_add_u64 v[162:163], v[36:37], 0, s[34:35]
	v_lshl_add_u64 v[164:165], v[34:35], 0, s[34:35]
	v_lshl_add_u64 v[166:167], v[32:33], 0, s[34:35]
	v_lshl_add_u64 v[168:169], v[30:31], 0, s[34:35]
	v_lshl_add_u64 v[170:171], v[28:29], 0, s[34:35]
	v_lshl_add_u64 v[172:173], v[26:27], 0, s[34:35]
	v_lshl_add_u64 v[174:175], v[22:23], 0, s[34:35]
	global_load_dword v124, v[160:161], off
	global_load_dword v125, v[162:163], off
	global_load_dword v126, v[164:165], off
	global_load_dword v127, v[166:167], off
	global_load_dword v128, v[168:169], off
	global_load_dword v129, v[170:171], off
	global_load_dword v130, v[172:173], off
	global_load_dword v131, v[174:175], off
	s_add_u32 s34, s34, 0x2c000
	s_addc_u32 s35, s35, 0
	s_add_u32 s36, s36, 64
	s_addc_u32 s37, s37, 0
	s_cmp_lg_u32 s34, 0xb0000
	s_waitcnt vmcnt(0)
	v_mul_f32_e32 v100, v100, v116
	ds_write_b32 v6, v100
	v_mul_f32_e32 v101, v101, v117
	ds_write_b32 v6, v101 offset:264
	v_mul_f32_e32 v102, v102, v118
	ds_write_b32 v6, v102 offset:528
	v_mul_f32_e32 v103, v103, v119
	ds_write_b32 v6, v103 offset:792
	v_mul_f32_e32 v104, v104, v120
	ds_write_b32 v6, v104 offset:1056
	v_mul_f32_e32 v105, v105, v121
	ds_write_b32 v6, v105 offset:1320
	v_mul_f32_e32 v106, v106, v122
	ds_write_b32 v6, v106 offset:1584
	v_mul_f32_e32 v107, v107, v123
	ds_write_b32 v6, v107 offset:1848
	v_mul_f32_e32 v108, v108, v124
	ds_write_b32 v6, v108 offset:2112
	v_mul_f32_e32 v109, v109, v125
	ds_write_b32 v6, v109 offset:2376
	v_mul_f32_e32 v110, v110, v126
	ds_write_b32 v6, v110 offset:2640
	v_mul_f32_e32 v111, v111, v127
	ds_write_b32 v6, v111 offset:2904
	v_mul_f32_e32 v112, v112, v128
	ds_write_b32 v6, v112 offset:3168
	v_mul_f32_e32 v113, v113, v129
	ds_write_b32 v6, v113 offset:3432
	v_mul_f32_e32 v114, v114, v130
	ds_write_b32 v6, v114 offset:3696
	v_mul_f32_e32 v115, v115, v131
	ds_write_b32 v6, v115 offset:3960
	v_add_u32_e32 v6, 0x1080, v6
	s_cbranch_scc1 .LBB0_31

; DI void transpose_item(const float* W, int N, const float* gain, bf16_t* WT, int ldk, int k0, int n0, int drow0, LAS float* scr, int lane) {
; #pragma unroll 8
;     for (int i = 0; i < 32; ++i) { const int kk = 2 * i + (lane >> 5); const float g = gain ? gain[k0 + kk] : 1.f; scr[kk * 33 + (lane & 31)] = W[(size_t)(k0 + kk) * N + n0 + (lane & 31)] * g; }
;     asm volatile("s_waitcnt lgkmcnt(0)" ::: "memory");
.LBB0_75:
	v_mov_b32_e32 v100, 1.0
	v_mov_b32_e32 v101, 1.0
	v_mov_b32_e32 v102, 1.0
	v_mov_b32_e32 v103, 1.0
	v_mov_b32_e32 v104, 1.0
	v_mov_b32_e32 v105, 1.0
	v_mov_b32_e32 v106, 1.0
	v_mov_b32_e32 v107, 1.0
	v_mov_b32_e32 v108, 1.0
	v_mov_b32_e32 v109, 1.0
	v_mov_b32_e32 v110, 1.0
	v_mov_b32_e32 v111, 1.0
	v_mov_b32_e32 v112, 1.0
	v_mov_b32_e32 v113, 1.0
	v_mov_b32_e32 v114, 1.0
	v_mov_b32_e32 v115, 1.0
	s_andn2_b64 vcc, exec, s[38:39]
	s_cbranch_vccnz .Ltr2_b_ng0
	v_lshl_add_u64 v[148:149], s[34:35], 0, v[6:7]
	v_lshl_add_u64 v[150:151], s[34:35], 0, v[22:23]
	global_load_dword v100, v[148:149], off
	global_load_dword v101, v[150:151], off offset:8
	global_load_dword v102, v[150:151], off offset:16
	global_load_dword v103, v[150:151], off offset:24
	global_load_dword v104, v[150:151], off offset:32
	global_load_dword v105, v[150:151], off offset:40
	global_load_dword v106, v[150:151], off offset:48
	global_load_dword v107, v[150:151], off offset:56
.Ltr2_b_ng0:
	v_lshl_add_u64 v[132:133], v[38:39], 0, s[36:37]
	v_lshl_add_u64 v[134:135], v[36:37], 0, s[36:37]
	v_lshl_add_u64 v[136:137], v[34:35], 0, s[36:37]
	v_lshl_add_u64 v[138:139], v[32:33], 0, s[36:37]
	v_lshl_add_u64 v[140:141], v[30:31], 0, s[36:37]
	v_lshl_add_u64 v[142:143], v[28:29], 0, s[36:37]
	v_lshl_add_u64 v[144:145], v[26:27], 0, s[36:37]
	v_lshl_add_u64 v[146:147], v[24:25], 0, s[36:37]
	global_load_dword v116, v[132:133], off
	global_load_dword v117, v[134:135], off
	global_load_dword v118, v[136:137], off
	global_load_dword v119, v[138:139], off
	global_load_dword v120, v[140:141], off
	global_load_dword v121, v[142:143], off
	global_load_dword v122, v[144:145], off
	global_load_dword v123, v[146:147], off
	s_add_u32 s36, s36, 0x10000
	s_addc_u32 s37, s37, 0
	s_add_u32 s34, s34, 64
	s_addc_u32 s35, s35, 0
	s_andn2_b64 vcc, exec, s[38:39]
	s_cbranch_vccnz .Ltr2_b_ng1
	v_lshl_add_u64 v[156:157], s[34:35], 0, v[6:7]
	v_lshl_add_u64 v[158:159], s[34:35], 0, v[22:23]
	global_load_dword v108, v[156:157], off
	global_load_dword v109, v[158:159], off offset:8
	global_load_dword v110, v[158:159], off offset:16
	global_load_dword v111, v[158:159], off offset:24
	global_load_dword v112, v[158:159], off offset:32
	global_load_dword v113, v[158:159], off offset:40
	global_load_dword v114, v[158:159], off offset:48
	global_load_dword v115, v[158:159], off offset:56
.Ltr2_b_ng1:
	v_lshl_add_u64 v[160:161], v[38:39], 0, s[36:37]
	v_lshl_add_u64 v[162:163], v[36:37], 0, s[36:37]
	v_lshl_add_u64 v[164:165], v[34:35], 0, s[36:37]
	v_lshl_add_u64 v[166:167], v[32:33], 0, s[36:37]
	v_lshl_add_u64 v[168:169], v[30:31], 0, s[36:37]
	v_lshl_add_u64 v[170:171], v[28:29], 0, s[36:37]
	v_lshl_add_u64 v[172:173], v[26:27], 0, s[36:37]
	v_lshl_add_u64 v[174:175], v[24:25], 0, s[36:37]
	global_load_dword v124, v[160:161], off
	global_load_dword v125, v[162:163], off
	global_load_dword v126, v[164:165], off
	global_load_dword v127, v[166:167], off
	global_load_dword v128, v[168:169], off
	global_load_dword v129, v[170:171], off
	global_load_dword v130, v[172:173], off
	global_load_dword v131, v[174:175], off
	s_add_u32 s36, s36, 0x10000
	s_addc_u32 s37, s37, 0
	s_add_u32 s34, s34, 64
	s_addc_u32 s35, s35, 0
	s_cmp_lg_u32 s36, 0x40000
	s_waitcnt vmcnt(0)
	v_mul_f32_e32 v100, v100, v116
	ds_write_b32 v21, v100
	v_mul_f32_e32 v101, v101, v117
	ds_write_b32 v21, v101 offset:264
	v_mul_f32_e32 v102, v102, v118
	ds_write_b32 v21, v102 offset:528
	v_mul_f32_e32 v103, v103, v119
	ds_write_b32 v21, v103 offset:792
	v_mul_f32_e32 v104, v104, v120
	ds_write_b32 v21, v104 offset:1056
	v_mul_f32_e32 v105, v105, v121
	ds_write_b32 v21, v105 offset:1320
	v_mul_f32_e32 v106, v106, v122
	ds_write_b32 v21, v106 offset:1584
	v_mul_f32_e32 v107, v107, v123
	ds_write_b32 v21, v107 offset:1848
	v_mul_f32_e32 v108, v108, v124
	ds_write_b32 v21, v108 offset:2112
	v_mul_f32_e32 v109, v109, v125
	ds_write_b32 v21, v109 offset:2376
	v_mul_f32_e32 v110, v110, v126
	ds_write_b32 v21, v110 offset:2640
	v_mul_f32_e32 v111, v111, v127
	ds_write_b32 v21, v111 offset:2904
	v_mul_f32_e32 v112, v112, v128
	ds_write_b32 v21, v112 offset:3168
	v_mul_f32_e32 v113, v113, v129
	ds_write_b32 v21, v113 offset:3432
	v_mul_f32_e32 v114, v114, v130
	ds_write_b32 v21, v114 offset:3696
	v_mul_f32_e32 v115, v115, v131
	ds_write_b32 v21, v115 offset:3960
	v_add_u32_e32 v21, 0x1080, v21
	s_cbranch_scc1 .LBB0_75

; DI void transpose_item(const float* W, int N, const float* gain, bf16_t* WT, int ldk, int k0, int n0, int drow0, LAS float* scr, int lane) {
; #pragma unroll 8
;     for (int i = 0; i < 32; ++i) { const int kk = 2 * i + (lane >> 5); const float g = gain ? gain[k0 + kk] : 1.f; scr[kk * 33 + (lane & 31)] = W[(size_t)(k0 + kk) * N + n0 + (lane & 31)] * g; }
;     asm volatile("s_waitcnt lgkmcnt(0)" ::: "memory");
.LBB0_96:
	v_mov_b32_e32 v100, 1.0
	v_mov_b32_e32 v101, 1.0
	v_mov_b32_e32 v102, 1.0
	v_mov_b32_e32 v103, 1.0
	v_mov_b32_e32 v104, 1.0
	v_mov_b32_e32 v105, 1.0
	v_mov_b32_e32 v106, 1.0
	v_mov_b32_e32 v107, 1.0
	v_mov_b32_e32 v108, 1.0
	v_mov_b32_e32 v109, 1.0
	v_mov_b32_e32 v110, 1.0
	v_mov_b32_e32 v111, 1.0
	v_mov_b32_e32 v112, 1.0
	v_mov_b32_e32 v113, 1.0
	v_mov_b32_e32 v114, 1.0
	v_mov_b32_e32 v115, 1.0
	s_andn2_b64 vcc, exec, s[28:29]
	s_cbranch_vccnz .Ltr2_c_ng0
	v_lshl_add_u64 v[148:149], s[38:39], 0, v[38:39]
	v_lshl_add_u64 v[150:151], s[38:39], 0, v[24:25]
	global_load_dword v100, v[148:149], off
	global_load_dword v101, v[150:151], off offset:8
	global_load_dword v102, v[150:151], off offset:16
	global_load_dword v103, v[150:151], off offset:24
	global_load_dword v104, v[150:151], off offset:32
	global_load_dword v105, v[150:151], off offset:40
	global_load_dword v106, v[150:151], off offset:48
	global_load_dword v107, v[150:151], off offset:56
.Ltr2_c_ng0:
	v_lshl_add_u64 v[132:133], v[40:41], 0, s[36:37]
	v_lshl_add_u64 v[134:135], v[36:37], 0, s[36:37]
	v_lshl_add_u64 v[136:137], v[34:35], 0, s[36:37]
	v_lshl_add_u64 v[138:139], v[32:33], 0, s[36:37]
	v_lshl_add_u64 v[140:141], v[30:31], 0, s[36:37]
	v_lshl_add_u64 v[142:143], v[28:29], 0, s[36:37]
	v_lshl_add_u64 v[144:145], v[26:27], 0, s[36:37]
	v_lshl_add_u64 v[146:147], v[22:23], 0, s[36:37]
	global_load_dword v116, v[132:133], off
	global_load_dword v117, v[134:135], off
	global_load_dword v118, v[136:137], off
	global_load_dword v119, v[138:139], off
	global_load_dword v120, v[140:141], off
	global_load_dword v121, v[142:143], off
	global_load_dword v122, v[144:145], off
	global_load_dword v123, v[146:147], off
	s_add_u32 s36, s36, 0x74000
	s_addc_u32 s37, s37, 0
	s_add_u32 s38, s38, 64
	s_addc_u32 s39, s39, 0
	s_andn2_b64 vcc, exec, s[28:29]
	s_cbranch_vccnz .Ltr2_c_ng1
	v_lshl_add_u64 v[156:157], s[38:39], 0, v[38:39]
	v_lshl_add_u64 v[158:159], s[38:39], 0, v[24:25]
	global_load_dword v108, v[156:157], off
	global_load_dword v109, v[158:159], off offset:8
	global_load_dword v110, v[158:159], off offset:16
	global_load_dword v111, v[158:159], off offset:24
	global_load_dword v112, v[158:159], off offset:32
	global_load_dword v113, v[158:159], off offset:40
	global_load_dword v114, v[158:159], off offset:48
	global_load_dword v115, v[158:159], off offset:56
.Ltr2_c_ng1:
	v_lshl_add_u64 v[160:161], v[40:41], 0, s[36:37]
	v_lshl_add_u64 v[162:163], v[36:37], 0, s[36:37]
	v_lshl_add_u64 v[164:165], v[34:35], 0, s[36:37]
	v_lshl_add_u64 v[166:167], v[32:33], 0, s[36:37]
	v_lshl_add_u64 v[168:169], v[30:31], 0, s[36:37]
	v_lshl_add_u64 v[170:171], v[28:29], 0, s[36:37]
	v_lshl_add_u64 v[172:173], v[26:27], 0, s[36:37]
	v_lshl_add_u64 v[174:175], v[22:23], 0, s[36:37]
	global_load_dword v124, v[160:161], off
	global_load_dword v125, v[162:163], off
	global_load_dword v126, v[164:165], off
	global_load_dword v127, v[166:167], off
	global_load_dword v128, v[168:169], off
	global_load_dword v129, v[170:171], off
	global_load_dword v130, v[172:173], off
	global_load_dword v131, v[174:175], off
	s_add_u32 s36, s36, 0x74000
	s_addc_u32 s37, s37, 0
	s_add_u32 s38, s38, 64
	s_addc_u32 s39, s39, 0
	s_cmp_lg_u32 s36, 0x1d0000
	s_waitcnt vmcnt(0)
	v_mul_f32_e32 v100, v100, v116
	ds_write_b32 v6, v100
	v_mul_f32_e32 v101, v101, v117
	ds_write_b32 v6, v101 offset:264
	v_mul_f32_e32 v102, v102, v118
	ds_write_b32 v6, v102 offset:528
	v_mul_f32_e32 v103, v103, v119
	ds_write_b32 v6, v103 offset:792
	v_mul_f32_e32 v104, v104, v120
	ds_write_b32 v6, v104 offset:1056
	v_mul_f32_e32 v105, v105, v121
	ds_write_b32 v6, v105 offset:1320
	v_mul_f32_e32 v106, v106, v122
	ds_write_b32 v6, v106 offset:1584
	v_mul_f32_e32 v107, v107, v123
	ds_write_b32 v6, v107 offset:1848
	v_mul_f32_e32 v108, v108, v124
	ds_write_b32 v6, v108 offset:2112
	v_mul_f32_e32 v109, v109, v125
	ds_write_b32 v6, v109 offset:2376
	v_mul_f32_e32 v110, v110, v126
	ds_write_b32 v6, v110 offset:2640
	v_mul_f32_e32 v111, v111, v127
	ds_write_b32 v6, v111 offset:2904
	v_mul_f32_e32 v112, v112, v128
	ds_write_b32 v6, v112 offset:3168
	v_mul_f32_e32 v113, v113, v129
	ds_write_b32 v6, v113 offset:3432
	v_mul_f32_e32 v114, v114, v130
	ds_write_b32 v6, v114 offset:3696
	v_mul_f32_e32 v115, v115, v131
	ds_write_b32 v6, v115 offset:3960
	v_add_u32_e32 v6, 0x1080, v6
	s_cbranch_scc1 .LBB0_96
	s_branch .LBB0_20
